# k13 plus: bf16(p) loop skipped on the 64 S5-building workgroups (others stride 192), weight-transpose items handed out in reverse wave order so the partial last round avoids those workgroups
# baseline (speedup 1.0000x reference)
; #define LAS __attribute__((address_space(3)))
; __device__ __forceinline__ void p0_prologue(const In& in, float* out, unsigned char* ws, LAS unsigned char* lds, int tid, int lane, int wave) {
;     const int G = gridDim.x, bx = blockIdx.x;
;     if (bx == 0) { unsigned* bw = (unsigned*)(ws + WS_BAR); for (int i = tid; i < BAR_WORDS; i += NTHREADS) bw[i] = 0u; }
;     for (int g = bx; g < NG; g += G) ssm_build(in, ws, lds, g, tid);
;     { float* st = (float*)(ws + WS_STAT) + MROWS; for (int i = bx * NTHREADS + tid; i < (ST_N - 1) * MROWS; i += G * NTHREADS) st[i] = 0.f; }
;     LAS float* scr = (LAS float*)(lds + wave * 16384);
;     const int gw = bx * NWAVES + wave, NGW = G * NWAVES;
;     constexpr int I_GU = (DM / 64) * (FF / 64), I_D = (FF / 64) * (DM / 64), I_IN = (DM / 64) * (NIN / 64), I_GLU = (SSMW / 64) * (SSMW / 64), I_SQ = (DM / 64) * (DM / 64), I_PP = (PLE / 64) * (DM / 64);
;     constexpr int NITEMS = 4 * I_GU + 2 * I_D + I_IN + I_GLU + 2 * I_SQ + I_PP;
;     ...
;     for (int it = gw; it < NITEMS * P0_REP; it += NGW) {
.LBB0_70:
	s_or_b64 exec, exec, s[6:7]
	s_load_dwordx16 s[52:67], s[0:1], 0x0
	s_load_dwordx16 s[36:51], s[0:1], 0x80
	s_load_dwordx16 s[4:19], s[0:1], 0xc0
	s_lshl_b32 s0, s2, 3
	s_lshl_b32 s26, s70, 3
	s_waitcnt lgkmcnt(0)
	v_writelane_b32 v255, s4, 4
	s_nop 1
	v_writelane_b32 v255, s5, 5
	v_writelane_b32 v255, s6, 6
	v_writelane_b32 v255, s7, 7
	v_writelane_b32 v255, s8, 8
	v_writelane_b32 v255, s9, 9
	v_writelane_b32 v255, s10, 10
	v_writelane_b32 v255, s11, 11
	v_writelane_b32 v255, s12, 12
	v_writelane_b32 v255, s13, 13
	v_writelane_b32 v255, s14, 14
	v_writelane_b32 v255, s15, 15
	v_writelane_b32 v255, s16, 16
	v_writelane_b32 v255, s17, 17
	v_writelane_b32 v255, s18, 18
	v_writelane_b32 v255, s19, 19
	s_nop 0
	v_readlane_b32 s1, v255, 3
	s_add_i32 s24, s1, s0
	s_cmpk_gt_i32 s24, 0x537f
	s_cbranch_scc1 .LBB0_191
	v_readlane_b32 s0, v255, 3
	s_lshl_b32 s0, s0, 14
	s_add_i32 s4, s0, 0
	v_and_b32_e32 v2, 7, v74
	v_mov_b32_e32 v15, 0
	v_lshl_add_u32 v4, v2, 11, s4
	v_lshlrev_b32_e32 v14, 3, v2
	v_lshlrev_b32_e32 v2, 4, v2
	v_mov_b32_e32 v3, v15
	v_lshrrev_b32_e32 v5, 1, v74
	v_lshl_add_u64 v[2:3], s[68:69], 0, v[2:3]
	s_mov_b64 s[0:1], 0xae00000
	v_and_b32_e32 v13, 60, v5
	v_lshl_add_u64 v[16:17], v[2:3], 0, s[0:1]
	v_bitop3_b32 v5, v5, v14, 60 bitop3:0x6c
	v_add_u32_e32 v76, 32, v13
	s_mov_b64 s[0:1], 0xa600000
	v_lshl_add_u32 v75, v5, 2, v4
	v_xor_b32_e32 v5, v76, v14
	v_lshl_add_u64 v[18:19], v[2:3], 0, s[0:1]
	s_mov_b64 s[0:1], 0x9000000
	v_lshl_add_u32 v77, v5, 2, v4
	v_lshl_add_u64 v[20:21], v[2:3], 0, s[0:1]
	v_lshl_add_u64 v[4:5], s[68:69], 0, v[14:15]
	s_mov_b64 s[0:1], 0x6400000
	v_and_b32_e32 v11, 60, v22
	v_lshl_add_u64 v[22:23], v[4:5], 0, s[0:1]
	s_mov_b64 s[0:1], 0x5c00000
	v_readlane_b32 s80, v255, 4
	v_lshl_add_u64 v[24:25], v[2:3], 0, s[0:1]
	s_mov_b64 s[0:1], 0x5a00000
	v_readlane_b32 s86, v255, 10
	v_readlane_b32 s87, v255, 11
	v_lshl_add_u64 v[26:27], v[2:3], 0, s[0:1]
	s_mov_b64 s[0:1], 0x4a00000
	s_cmp_lg_u64 s[86:87], 0
	v_lshl_add_u64 v[28:29], v[2:3], 0, s[0:1]
	s_mov_b64 s[0:1], 0x3400000
	s_cselect_b64 s[6:7], -1, 0
	s_cmp_lg_u64 s[50:51], 0
	v_lshrrev_b32_e32 v12, 4, v74
	v_lshl_add_u64 v[30:31], v[2:3], 0, s[0:1]
	s_mov_b64 s[0:1], 0x800000
	v_lshlrev_b32_e32 v14, 2, v11
	v_readlane_b32 s90, v255, 14
	v_readlane_b32 s91, v255, 15
	s_cselect_b64 s[18:19], -1, 0
	s_add_u32 s3, s46, 0xfffff000
	v_lshl_add_u64 v[32:33], v[2:3], 0, s[0:1]
	v_lshl_add_u64 v[34:35], s[90:91], 0, v[14:15]
	s_addc_u32 s12, s47, -1
	v_lshlrev_b32_e32 v14, 2, v12
	s_mov_b32 s0, 0xfffd8810
	s_cmp_lg_u64 s[64:65], 0
	v_lshl_add_u64 v[2:3], s[86:87], 0, v[14:15]
	s_mov_b32 s1, -1
	s_cselect_b64 s[28:29], -1, 0
	s_cmp_lg_u64 s[56:57], 0
	v_lshlrev_b32_e32 v36, 4, v36
	v_lshl_add_u64 v[38:39], v[2:3], 0, s[0:1]
	v_mul_u32_u24_e32 v2, 0x5800, v12
	s_mov_b32 s0, 0xfffeb010
	s_mov_b32 s8, 0xffff7c10
	v_readlane_b32 s81, v255, 5
	v_readlane_b32 s82, v255, 6
	v_readlane_b32 s83, v255, 7
	s_cselect_b64 s[30:31], -1, 0
	v_mov_b32_e32 v37, v15
	v_mul_hi_u32_u24_e32 v3, 0x5800, v12
	v_or_b32_e32 v2, v2, v36
	v_or_b32_e32 v4, 32, v14
	v_mov_b32_e32 v5, v15
	s_mov_b32 s1, -1
	v_lshl_add_u64 v[6:7], s[64:65], 0, v[14:15]
	s_mov_b32 s9, -1
	s_add_u32 s46, s56, 32
	s_mov_b32 s5, 0
	v_lshl_add_u32 v78, v12, 8, s4
	v_add_u32_e32 v79, 0xffff620c, v12
	v_or_b32_e32 v80, 0xffff6200, v12
	v_or_b32_e32 v81, 0xffff6208, v12
	v_add_u32_e32 v82, 0xffff6204, v12
	v_add_u32_e32 v83, 0xffff780c, v12
	v_or_b32_e32 v84, 0xffff7808, v12
	v_add_u32_e32 v85, 0xffff7804, v12
	v_or_b32_e32 v86, 0xffff7800, v12
	v_add_u32_e32 v87, 12, v12
	s_movk_i32 s13, 0x5800
	v_lshl_add_u64 v[40:41], s[82:83], 0, v[2:3]
	v_or_b32_e32 v88, 8, v12
	v_lshl_add_u64 v[42:43], s[50:51], 0, v[4:5]
	v_add_u32_e32 v89, 4, v12
	v_lshl_add_u64 v[44:45], s[80:81], 0, v[2:3]
	v_add_u32_e32 v90, 0xffffac0c, v12
	v_or_b32_e32 v91, 0xffffac00, v12
	v_or_b32_e32 v92, 0xffffac08, v12
	v_add_u32_e32 v93, 0xffffac04, v12
	v_add_u32_e32 v94, 0xffff5c0c, v12
	v_or_b32_e32 v95, 0xffff5c08, v12
	v_add_u32_e32 v96, 0xffff5c04, v12
	v_or_b32_e32 v97, 0xffff5c00, v12
	v_add_u32_e32 v98, 0xffffdf0c, v12
	v_or_b32_e32 v99, 0xffffdf00, v12
	v_or_b32_e32 v100, 0xffffdf08, v12
	v_add_u32_e32 v101, 0xffffdf04, v12
	v_lshl_add_u64 v[46:47], v[6:7], 0, s[8:9]
	v_add_u32_e32 v102, 0xffffd40c, v12
	v_or_b32_e32 v103, 0xffffd408, v12
	v_add_u32_e32 v104, 0xffffd404, v12
	v_or_b32_e32 v105, 0xffffd400, v12
	v_lshl_add_u64 v[48:49], s[60:61], 0, v[2:3]
	v_lshl_add_u64 v[50:51], s[56:57], 0, v[4:5]
	s_addc_u32 s47, s57, 0
	s_mov_b64 s[50:51], 0x20000
	s_movk_i32 s14, 0x2c00
	s_mov_b64 s[56:57], 0x58000
	s_mov_b32 s15, 0xc3e00000
	s_mov_b64 s[76:77], 0x10000
	s_mov_b64 s[78:79], 0x40000
	v_mov_b32_e32 v106, 0x160000
	v_mov_b32_e32 v107, 0x43e00000
	s_mov_b32 s16, s24
	s_cmpk_gt_u32 s26, 0x5380
	s_cbranch_scc1 .Ltr_keep
	s_sub_i32 s16, s26, s24
	s_add_i32 s16, s16, -1
.Ltr_keep:
	v_lshl_add_u64 v[52:53], s[82:83], 0, v[36:37]
	v_lshl_add_u64 v[54:55], s[80:81], 0, v[36:37]
	v_lshl_add_u64 v[56:57], v[14:15], 0, s[0:1]
	v_lshl_add_u64 v[58:59], s[60:61], 0, v[36:37]
	v_lshl_add_u64 v[60:61], s[58:59], 0, v[36:37]
	v_readlane_b32 s84, v255, 8
	v_readlane_b32 s85, v255, 9
	v_readlane_b32 s88, v255, 12
	v_readlane_b32 s89, v255, 13
	v_readlane_b32 s92, v255, 16
	v_readlane_b32 s93, v255, 17
	v_readlane_b32 s94, v255, 18
	v_readlane_b32 s95, v255, 19
	s_branch .LBB0_74

; __device__ __forceinline__ unsigned cvt_pk_bf16(float lo, float hi) { unsigned r; asm volatile("v_cvt_pk_bf16_f32 %0, %1, %2" : "=v"(r) : "v"(lo), "v"(hi)); return r; }
; #define GAS __attribute__((address_space(1)))
; __device__ __forceinline__ void p0_prologue(const In& in, float* out, unsigned char* ws, LAS unsigned char* lds, int tid, int lane, int wave) {
;     ...
;     { const GAS f32x4* ps = (const GAS f32x4*)in.p; GAS v2u* o = (GAS v2u*)(ws + WS_PB);
;       for (int i = bx * NTHREADS + tid; i < MROWS * PLE / 4; i += G * NTHREADS) { const f32x4 v = ps[i]; v2u w; w.x = cvt_pk_bf16(v.x, v.y); w.y = cvt_pk_bf16(v.z, v.w); o[i] = w; } }
.Lpb_entry:
	s_mov_b32 s3, s2
	s_mov_b32 s12, s70
	s_cmpk_lg_u32 s70, 0x100
	s_cbranch_scc1 .Lpb_norm
	s_cmpk_lt_u32 s2, 64
	s_cbranch_scc1 .LBB0_199
	s_sub_i32 s3, s2, 64
	s_movk_i32 s12, 0xc0
	v_add_u32_e32 v10, 0xffff8000, v10
.Lpb_norm:
	s_lshl_b32 s4, s12, 9
	v_ashrrev_i32_e32 v11, 31, v10
	v_mov_b32_e32 v4, s54
	v_mov_b32_e32 v5, s55
	v_lshl_add_u64 v[2:3], v[10:11], 3, s[68:69]
	s_mov_b64 s[6:7], 0xb000000
	s_ashr_i32 s5, s4, 31
	v_lshl_add_u64 v[2:3], v[2:3], 0, s[6:7]
	s_lshl_b64 s[6:7], s[4:5], 3
	v_lshl_add_u64 v[4:5], v[10:11], 4, v[4:5]
	s_lshl_b64 s[8:9], s[4:5], 4
	s_mul_i32 s10, s12, 7
.Lpb_batch:
	s_add_i32 s11, s3, s10
	s_cmpk_ge_i32 s11, 0x1000
	s_cbranch_scc1 .Lpb_tail
	global_load_dwordx4 v[16:19], v[4:5], off
	v_lshl_add_u64 v[4:5], v[4:5], 0, s[8:9]
	global_load_dwordx4 v[20:23], v[4:5], off
	v_lshl_add_u64 v[4:5], v[4:5], 0, s[8:9]
	global_load_dwordx4 v[24:27], v[4:5], off
	v_lshl_add_u64 v[4:5], v[4:5], 0, s[8:9]
	global_load_dwordx4 v[28:31], v[4:5], off
	v_lshl_add_u64 v[4:5], v[4:5], 0, s[8:9]
	global_load_dwordx4 v[32:35], v[4:5], off
	v_lshl_add_u64 v[4:5], v[4:5], 0, s[8:9]
	global_load_dwordx4 v[36:39], v[4:5], off
	v_lshl_add_u64 v[4:5], v[4:5], 0, s[8:9]
	global_load_dwordx4 v[40:43], v[4:5], off
	v_lshl_add_u64 v[4:5], v[4:5], 0, s[8:9]
	global_load_dwordx4 v[44:47], v[4:5], off
	v_lshl_add_u64 v[4:5], v[4:5], 0, s[8:9]
	s_waitcnt vmcnt(7)
	v_cvt_pk_bf16_f32 v48, v16, v17
	v_cvt_pk_bf16_f32 v49, v18, v19
	global_store_dwordx2 v[2:3], v[48:49], off
	v_lshl_add_u64 v[2:3], v[2:3], 0, s[6:7]
	s_waitcnt vmcnt(7)
	v_cvt_pk_bf16_f32 v50, v20, v21
	v_cvt_pk_bf16_f32 v51, v22, v23
	global_store_dwordx2 v[2:3], v[50:51], off
	v_lshl_add_u64 v[2:3], v[2:3], 0, s[6:7]
	s_waitcnt vmcnt(7)
	v_cvt_pk_bf16_f32 v52, v24, v25
	v_cvt_pk_bf16_f32 v53, v26, v27
	global_store_dwordx2 v[2:3], v[52:53], off
	v_lshl_add_u64 v[2:3], v[2:3], 0, s[6:7]
	s_waitcnt vmcnt(7)
	v_cvt_pk_bf16_f32 v54, v28, v29
	v_cvt_pk_bf16_f32 v55, v30, v31
	global_store_dwordx2 v[2:3], v[54:55], off
	v_lshl_add_u64 v[2:3], v[2:3], 0, s[6:7]
	s_waitcnt vmcnt(7)
	v_cvt_pk_bf16_f32 v56, v32, v33
	v_cvt_pk_bf16_f32 v57, v34, v35
	global_store_dwordx2 v[2:3], v[56:57], off
	v_lshl_add_u64 v[2:3], v[2:3], 0, s[6:7]
	s_waitcnt vmcnt(7)
	v_cvt_pk_bf16_f32 v58, v36, v37
	v_cvt_pk_bf16_f32 v59, v38, v39
	global_store_dwordx2 v[2:3], v[58:59], off
	v_lshl_add_u64 v[2:3], v[2:3], 0, s[6:7]
	s_waitcnt vmcnt(7)
	v_cvt_pk_bf16_f32 v60, v40, v41
	v_cvt_pk_bf16_f32 v61, v42, v43
	global_store_dwordx2 v[2:3], v[60:61], off
	v_lshl_add_u64 v[2:3], v[2:3], 0, s[6:7]
	s_waitcnt vmcnt(7)
	v_cvt_pk_bf16_f32 v62, v44, v45
	v_cvt_pk_bf16_f32 v63, v46, v47
	global_store_dwordx2 v[2:3], v[62:63], off
	v_lshl_add_u64 v[2:3], v[2:3], 0, s[6:7]
	s_lshl_b32 s11, s12, 3
	s_add_i32 s3, s3, s11
	s_branch .Lpb_batch
.Lpb_tail:
	s_cmpk_ge_i32 s3, 0x1000
	s_cbranch_scc1 .LBB0_199
	global_load_dwordx4 v[16:19], v[4:5], off
	v_lshl_add_u64 v[4:5], v[4:5], 0, s[8:9]
	s_add_i32 s3, s3, s12
	s_waitcnt vmcnt(0)
	v_cvt_pk_bf16_f32 v48, v16, v17
	v_cvt_pk_bf16_f32 v49, v18, v19
	global_store_dwordx2 v[2:3], v[48:49], off
	v_lshl_add_u64 v[2:3], v[2:3], 0, s[6:7]
	s_branch .Lpb_tail
